# ssm pass-1 chunk top: the second batch of four row-rstd loads is issued with the first (one round trip per chunk instead of two), counted waits
# baseline (speedup 1.0000x reference)
; template <int PASS> __device__ __forceinline__ void ssm_phase(int j, LAS unsigned char* lds, int lane, int wave) { KARGS;
;     ...
;             { const int t = 64 * c + lane; float ssq = 0.f;
; #pragma unroll
;               for (int q = 0; q < 8; ++q) { const f32x4 v = *(const f32x4*)(rsp + (size_t)t * 64 + 4 * q); ssq += (v[0] + v[1]) + (v[2] + v[3]); }
;               rsL[lane] = rsqrtf(ssq * (1.0f / D) + EPS); }
.LBB0_233:
	s_add_i32 s4, s12, s16
	s_cmp_eq_u32 s12, 8
	s_cselect_b32 s36, s17, s4
	s_lshl_b32 s37, s36, 6
	v_or_b32_e32 v36, s37, v40
	v_ashrrev_i32_e32 v37, 31, v36
	v_lshlrev_b64 v[36:37], 8, v[36:37]
	v_lshl_add_u64 v[80:81], s[42:43], 0, v[36:37]
	global_load_dwordx4 v[36:39], v[80:81], off offset:48
	global_load_dwordx4 v[68:71], v[80:81], off offset:32
	global_load_dwordx4 v[72:75], v[80:81], off
	global_load_dwordx4 v[76:79], v[80:81], off offset:16
	global_load_dwordx4 v[100:103], v[80:81], off offset:112
	global_load_dwordx4 v[104:107], v[80:81], off offset:96
	global_load_dwordx4 v[108:111], v[80:81], off offset:80
	global_load_dwordx4 v[112:115], v[80:81], off offset:64
	s_or_b32 s45, s37, 16
	s_mov_b32 s46, 0
	s_mov_b64 s[10:11], -1
	s_waitcnt vmcnt(7)
	v_add_f32_e32 v86, v36, v37
	v_add_f32_e32 v88, v38, v39
	s_waitcnt vmcnt(5)
	v_mov_b32_e32 v64, v72
	s_waitcnt vmcnt(4)
	v_mov_b32_e32 v65, v76
	v_mov_b32_e32 v76, v73
	v_mov_b32_e32 v72, v74
	v_mov_b32_e32 v73, v78
	v_mov_b32_e32 v78, v75
	v_pk_add_f32 v[64:65], v[64:65], v[76:77]
	v_pk_add_f32 v[72:73], v[72:73], v[78:79]
	s_nop 0
	v_pk_add_f32 v[72:73], v[64:65], v[72:73]
	v_mov_b32_e32 v64, 0
	v_add_f32_e32 v65, 0, v72
	v_add_f32_e32 v82, v65, v73
	v_mov_b32_e32 v72, v69
	v_mov_b32_e32 v73, v70
	v_mov_b32_e32 v69, v71
	v_pk_add_f32 v[68:69], v[72:73], v[68:69]
	v_mov_b32_e32 v65, v64
	v_pk_add_f32 v[84:85], v[68:69], v[68:69] op_sel:[0,1] op_sel_hi:[1,0]
	s_waitcnt vmcnt(0)
	v_mov_b64_e32 v[36:37], v[100:101]
	v_mov_b64_e32 v[38:39], v[102:103]
	v_mov_b64_e32 v[68:69], v[104:105]
	v_mov_b64_e32 v[70:71], v[106:107]
	v_mov_b64_e32 v[72:73], v[108:109]
	v_mov_b64_e32 v[74:75], v[110:111]
	v_mov_b64_e32 v[76:77], v[112:113]
	v_mov_b64_e32 v[78:79], v[114:115]
	v_add_f32_e32 v68, v68, v69
	v_add_f32_e32 v70, v70, v71
	v_mov_b32_e32 v83, v76
	v_mov_b32_e32 v85, v77
	v_mov_b32_e32 v87, v78
	v_mov_b32_e32 v89, v79
	v_pk_add_f32 v[76:77], v[82:83], v[84:85]
	v_pk_add_f32 v[78:79], v[86:87], v[88:89]
	v_mov_b32_e32 v69, v38
	v_pk_add_f32 v[76:77], v[76:77], v[78:79]
	v_mov_b32_e32 v78, v73
	v_mov_b32_e32 v79, v74
	v_mov_b32_e32 v73, v75
	v_pk_add_f32 v[72:73], v[78:79], v[72:73]
	v_pk_add_f32 v[76:77], v[76:77], v[76:77] op_sel:[0,1] op_sel_hi:[1,0]
	v_pk_add_f32 v[72:73], v[72:73], v[72:73] op_sel:[0,1] op_sel_hi:[1,0]
	v_mov_b32_e32 v77, v36
	v_mov_b32_e32 v73, v37
	v_mov_b32_e32 v71, v39
	v_pk_add_f32 v[36:37], v[76:77], v[72:73]
	v_pk_add_f32 v[38:39], v[68:69], v[70:71]
	s_nop 0
	v_pk_add_f32 v[36:37], v[36:37], v[38:39]
	s_nop 0
	v_add_f32_e32 v36, v36, v37
	v_fmamk_f32 v36, v36, 0x3a000000, v223
	v_cmp_gt_f32_e32 vcc, s97, v36
	v_mul_f32_e32 v37, 0x4b800000, v36
	s_nop 0
	v_cndmask_b32_e32 v36, v36, v37, vcc
	v_rsq_f32_e32 v36, v36
	s_nop 0
	v_mul_f32_e32 v37, 0x45800000, v36
	v_cndmask_b32_e32 v36, v36, v37, vcc
	ds_write_b32 v55, v36 offset:16384
	s_waitcnt lgkmcnt(0)
